# idle workgroups' weight-prep input loads (f32 weights, cache rows: read once) non-temporal
# baseline (speedup 1.0000x reference)
.LBB0_1247:
	s_or_saveexec_b64 s[8:9], s[8:9]
	v_lshlrev_b32_e32 v28, 6, v7
	s_xor_b64 exec, exec, s[8:9]
	s_cbranch_execz .LBB0_1249
	v_or_b32_e32 v7, v28, v5
	v_mad_u64_u32 v[20:21], s[2:3], v18, v7, 0
	v_lshl_add_u64 v[14:15], v[20:21], 2, v[14:15]
	v_mov_b32_e32 v17, v113
	v_lshl_add_u64 v[14:15], v[16:17], 2, v[14:15]
	v_mov_b32_e32 v7, v113
	v_lshl_add_u64 v[20:21], v[14:15], 0, v[6:7]
	v_lshlrev_b32_e32 v112, 3, v18
	v_lshl_add_u64 v[30:31], v[112:113], 2, v[20:21]
	global_load_dwordx4 v[14:17], v[20:21], off nt
	v_lshlrev_b32_e32 v112, 4, v18
	global_load_dwordx4 v[30:33], v[30:31], off nt
	v_lshl_add_u64 v[34:35], v[112:113], 2, v[20:21]
	v_mul_u32_u24_e32 v7, 24, v18
	global_load_dwordx4 v[34:37], v[34:35], off nt
	v_lshlrev_b32_e32 v112, 2, v7
	v_lshl_add_u64 v[38:39], v[20:21], 0, v[112:113]
	global_load_dwordx4 v[38:41], v[38:39], off nt
	v_lshlrev_b32_e32 v112, 5, v18
	v_lshl_add_u64 v[42:43], v[112:113], 2, v[20:21]
	v_mul_u32_u24_e32 v7, 40, v18
	global_load_dwordx4 v[42:45], v[42:43], off nt
	v_lshlrev_b32_e32 v112, 2, v7
	v_lshl_add_u64 v[46:47], v[20:21], 0, v[112:113]
	v_mul_u32_u24_e32 v7, 48, v18
	global_load_dwordx4 v[46:49], v[46:47], off nt
	v_lshlrev_b32_e32 v112, 2, v7
	v_lshl_add_u64 v[50:51], v[20:21], 0, v[112:113]
	v_mul_u32_u24_e32 v7, 56, v18
	global_load_dwordx4 v[50:53], v[50:51], off nt
	v_lshlrev_b32_e32 v112, 2, v7
	v_lshl_add_u64 v[18:19], v[20:21], 0, v[112:113]
	global_load_dwordx4 v[18:21], v[18:19], off nt
	v_add_u32_e32 v7, 0x420, v26
	s_waitcnt vmcnt(7)
	ds_write2_b32 v26, v14, v15 offset1:1
	ds_write2_b32 v26, v16, v17 offset0:2 offset1:3
	s_waitcnt vmcnt(6)
	ds_write2_b32 v7, v30, v31 offset1:1
	v_add_u32_e32 v7, 0x428, v26
	ds_write2_b32 v7, v32, v33 offset1:1
	v_add_u32_e32 v7, 0x840, v26
	s_waitcnt vmcnt(5)
	ds_write2_b32 v7, v34, v35 offset1:1
	v_add_u32_e32 v7, 0x848, v26
	ds_write2_b32 v7, v36, v37 offset1:1
	v_add_u32_e32 v7, 0xc60, v26
	s_waitcnt vmcnt(4)
	ds_write2_b32 v7, v38, v39 offset1:1
	v_add_u32_e32 v7, 0xc68, v26
	ds_write2_b32 v7, v40, v41 offset1:1
	v_add_u32_e32 v7, 0x1080, v26
	s_waitcnt vmcnt(3)
	ds_write2_b32 v7, v42, v43 offset1:1
	v_add_u32_e32 v7, 0x1088, v26
	ds_write2_b32 v7, v44, v45 offset1:1
	v_add_u32_e32 v7, 0x14a0, v26
	s_waitcnt vmcnt(2)
	ds_write2_b32 v7, v46, v47 offset1:1
	v_add_u32_e32 v7, 0x14a8, v26
	ds_write2_b32 v7, v48, v49 offset1:1
	v_add_u32_e32 v7, 0x18c0, v26
	s_waitcnt vmcnt(1)
	ds_write2_b32 v7, v50, v51 offset1:1
	v_add_u32_e32 v7, 0x18c8, v26
	ds_write2_b32 v7, v52, v53 offset1:1
	v_add_u32_e32 v7, 0x1ce0, v26
	s_waitcnt vmcnt(0)
	ds_write2_b32 v7, v18, v19 offset1:1
	v_add_u32_e32 v7, 0x1ce8, v26
	ds_write2_b32 v7, v20, v21 offset1:1

.LBB0_1268:
	s_or_b64 exec, exec, s[16:17]
	global_load_dwordx4 v[8:11], v[0:1], off nt
	global_load_dwordx4 v[12:15], v[0:1], off offset:16 nt
	v_add_u32_e32 v7, s28, v7
	v_add_u32_e32 v0, 0x24000, v7
	s_mov_b32 s2, 0x63fff
	v_cmp_lt_i32_e32 vcc, s2, v0
	s_or_b64 s[12:13], vcc, s[12:13]
	v_add_u32_e32 v6, s29, v6
	s_waitcnt vmcnt(1)
	v_cvt_pk_bf16_f32 v8, v8, v9
	v_cvt_pk_bf16_f32 v9, v10, v11
	s_waitcnt vmcnt(0)
	v_cvt_pk_bf16_f32 v10, v12, v13
	v_cvt_pk_bf16_f32 v11, v14, v15
	global_store_dwordx4 v[2:3], v[8:11], off sc1
	s_andn2_b64 exec, exec, s[12:13]
	s_cbranch_execz .LBB0_1289
